# static priority raise for waves 4-7 (the serial state-update chain) during the SSD scan phase, back to 0 at the phase end
# baseline (speedup 1.0000x reference)
.LBB0_586:
	v_readlane_b32 s2, v255, 0
	v_readlane_b32 s3, v255, 1
	s_mov_b64 s[0:1], -1
	s_and_b64 vcc, exec, s[2:3]
	s_cbranch_vccz .LBB0_688
	v_readlane_b32 s0, v254, 14
	v_writelane_b32 v255, s44, 6
	v_mov_b32_e32 v162, v0
	v_readlane_b32 s1, v254, 15
	v_writelane_b32 v255, s45, 7
	s_andn2_b64 vcc, exec, s[0:1]
	v_readfirstlane_b32 s0, v162
	s_cbranch_vccnz .LBB0_643
	v_readlane_b32 s12, v255, 6
	s_ashr_i32 s1, s0, 6
	s_lshl_b32 s2, s12, 6
	v_readlane_b32 s13, v255, 7
	v_writelane_b32 v255, s2, 13
	s_and_b32 s2, s1, 3
	s_and_b32 s3, s1, 1
	s_cmp_gt_i32 s1, 3
	s_mov_b32 s13, s85
	s_cselect_b64 s[68:69], -1, 0
	s_lshl_b64 s[4:5], s[12:13], 11
	v_writelane_b32 v255, s4, 16
	s_mul_hi_u32 s8, s12, 0x6000
	s_mul_i32 s9, s12, 0x6000
	v_writelane_b32 v255, s5, 17
	s_lshl_b32 s4, s2, 5
	v_writelane_b32 v255, s4, 14
	s_lshl_b32 s4, s2, 6
	s_add_i32 s4, s4, 0
	s_add_i32 s5, s4, 0x1e400
	s_cmp_eq_u32 s1, 3
	v_writelane_b32 v255, s5, 18
	s_cselect_b64 s[6:7], -1, 0
	v_writelane_b32 v255, s6, 11
	s_cmp_lg_u32 s1, 3
	s_cselect_b64 s[78:79], -1, 0
	v_writelane_b32 v255, s7, 12
	s_lshl_b32 s5, s3, 5
	v_writelane_b32 v255, s5, 10
	s_lshl_b32 s5, s1, 4
	s_lshl_b64 s[10:11], s[12:13], 5
	s_and_b32 s28, s5, 32
	v_writelane_b32 v255, s10, 8
	s_mul_hi_u32 s6, s12, 0x18000
	s_mul_i32 s7, s12, 0x18000
	v_writelane_b32 v255, s11, 9
	s_lshl_b32 s10, s28, 1
	s_add_u32 s10, s92, s10
	v_writelane_b32 v255, s10, 19
	s_addc_u32 s10, s93, 0
	s_cmp_gt_i32 s1, 2
	v_writelane_b32 v255, s10, 20
	s_cselect_b64 s[90:91], -1, 0
	s_ashr_i32 s10, s0, 2
	s_andn2_b32 s10, s10, 31
	s_add_i32 s5, s5, 16
	v_writelane_b32 v255, s10, 21
	s_and_b32 s10, s5, 0xffffffe0
	v_writelane_b32 v255, s10, 22
	s_and_b32 s10, s1, 2
	v_writelane_b32 v255, s10, 23
	s_mov_b32 s10, s12
	v_writelane_b32 v255, s10, 6
	v_readlane_b32 s80, v253, 8
	s_nop 0
	v_writelane_b32 v255, s11, 7
	s_lshl_b64 s[10:11], s[12:13], 8
	v_readlane_b32 s12, v253, 12
	v_readlane_b32 s13, v253, 13
	v_readlane_b32 s14, v253, 14
	v_readlane_b32 s15, v253, 15
	v_readlane_b32 s16, v253, 16
	v_readlane_b32 s17, v253, 17
	v_readlane_b32 s18, v253, 18
	v_readlane_b32 s19, v253, 19
	s_bitcmp1_b32 s1, 0
	v_readlane_b32 s20, v253, 20
	v_readlane_b32 s21, v253, 21
	v_readlane_b32 s22, v253, 22
	v_readlane_b32 s23, v253, 23
	s_mov_b64 s[12:13], s[16:17]
	v_writelane_b32 v255, s10, 24
	s_cselect_b64 s[54:55], -1, 0
	s_lshl_b32 s1, s2, 7
	s_mov_b64 s[14:15], s[18:19]
	s_mov_b64 s[16:17], s[20:21]
	v_writelane_b32 v255, s11, 25
	v_readlane_b32 s24, v253, 24
	v_readlane_b32 s25, v253, 25
	v_readlane_b32 s26, v253, 26
	v_readlane_b32 s27, v253, 27
	s_mov_b64 s[18:19], s[22:23]
	s_add_u32 s1, s16, s1
	v_writelane_b32 v255, s1, 26
	s_addc_u32 s1, s17, 0
	v_readlane_b32 s12, v253, 28
	v_readlane_b32 s24, v253, 40
	v_readlane_b32 s25, v253, 41
	s_add_u32 s56, s24, s7
	v_readlane_b32 s26, v253, 42
	s_addc_u32 s57, s25, s6
	v_readlane_b32 s27, v253, 43
	s_add_u32 s58, s26, s9
	v_writelane_b32 v255, s1, 27
	s_addc_u32 s59, s27, s8
	s_add_i32 s1, s4, 0x1a000
	v_writelane_b32 v255, s1, 28
	s_lshl_b32 s1, s3, 7
	v_writelane_b32 v255, s1, 29
	s_lshl_b32 s1, s5, 2
	s_and_b32 s1, s1, 0xffffff80
	v_writelane_b32 v255, s1, 30
	s_and_b32 s0, s0, 0xffffff80
	v_writelane_b32 v255, s0, 31
	v_readlane_b32 s13, v253, 29
	v_readlane_b32 s14, v253, 30
	v_readlane_b32 s15, v253, 31
	v_readlane_b32 s16, v253, 32
	v_readlane_b32 s17, v253, 33
	v_readlane_b32 s18, v253, 34
	v_readlane_b32 s19, v253, 35
	v_readlane_b32 s20, v253, 36
	v_readlane_b32 s21, v253, 37
	v_readlane_b32 s22, v253, 38
	v_readlane_b32 s23, v253, 39
	v_readfirstlane_b32 vcc_lo, v0
	s_nop 3
	s_cmp_lt_u32 vcc_lo, 0x100
	s_cbranch_scc1 .Lscanprio_skip
	s_setprio 2
.Lscanprio_skip:
	s_branch .LBB0_591
.LBB0_589:
	s_lshl_b64 s[0:1], s[0:1], 15
	s_add_u32 s0, s2, s0
	v_readlane_b32 s2, v255, 14
	s_addc_u32 s1, s3, s1
	s_lshl_b32 s2, s2, 2
	s_add_u32 s0, s0, s2
	s_addc_u32 s1, s1, 0
	v_lshlrev_b32_e32 v194, 2, v170
	v_lshl_add_u64 v[2:3], s[0:1], 0, v[194:195]
	v_lshlrev_b32_e32 v194, 9, v163
	v_lshl_add_u64 v[2:3], v[2:3], 0, v[194:195]
	global_store_dwordx4 v[2:3], v[66:69], off
	global_store_dwordx4 v[2:3], v[70:73], off offset:32
	global_store_dwordx4 v[2:3], v[74:77], off offset:64
	global_store_dwordx4 v[2:3], v[78:81], off offset:96
	v_add_co_u32_e32 v2, vcc, 0x4000, v2
	s_nop 1
	v_addc_co_u32_e32 v3, vcc, 0, v3, vcc
	global_store_dwordx4 v[2:3], v[82:85], off
	global_store_dwordx4 v[2:3], v[86:89], off offset:32
	global_store_dwordx4 v[2:3], v[90:93], off offset:64
	global_store_dwordx4 v[2:3], v[94:97], off offset:96

.LBB0_643:
	s_setprio 0
	s_waitcnt vmcnt(0)
	v_readlane_b32 s76, v254, 49
	v_readlane_b32 s77, v254, 50
	s_waitcnt lgkmcnt(0)
	s_barrier
	s_and_saveexec_b64 s[30:31], s[76:77]
	v_readlane_b32 s44, v255, 6
	v_readlane_b32 s45, v255, 7
	s_cbranch_execz .LBB0_687
	v_readlane_b32 s34, v253, 9
	v_readlane_b32 s0, v254, 43
	v_readlane_b32 s35, v253, 10
	v_readlane_b32 s33, v253, 11
	v_mov_b32_e32 v2, s0
	s_waitcnt vmcnt(0) expcnt(0) lgkmcnt(0)
	ds_read_b32 v4, v2
	v_readlane_b32 s0, v254, 44
	s_waitcnt lgkmcnt(0)
	v_cmp_ne_u32_e32 vcc, 0, v4
	v_mov_b32_e32 v2, s0
	ds_read_b32 v2, v2
	s_cbranch_vccnz .LBB0_658
	v_readlane_b32 s0, v253, 6
	v_readlane_b32 s1, v253, 7
	s_load_dwordx2 s[4:5], s[0:1], 0x4
	s_add_u32 s0, s34, 0x1000
	s_addc_u32 s1, s35, 0
	s_add_u32 s2, s34, 0x1100
	s_addc_u32 s3, s35, 0
	s_waitcnt lgkmcnt(0)
	s_mul_i32 s26, s4, s88
	s_add_u32 s4, s34, 0x1200
	s_mul_i32 s26, s26, s5
	s_addc_u32 s5, s35, 0
	s_add_u32 s6, s34, 0x1300
	s_addc_u32 s7, s35, 0
	s_mov_b32 s27, 1
	s_mov_b64 s[8:9], 0
	s_branch .LBB0_648
